# speedup vs baseline: 1.0010x; 1.0010x over previous
; DEVI int crow(int r, int hi) { return (r & 3) + 8 * (r >> 2) + 4 * hi; }
; DEVI float xor1(float v) { return dppf<0xB1, 0xF>(v, v); }
;   DEVI void operator()(f32x16* acc, int mrow, int pn, int r32, int hi, char* slice) const {
;     ...
;       for (int j = 0; j < 4; ++j) {
;         const float g = gain[j * 32 + r32];
;         const int fi = (j & 1) * 16 + (r32 >> 1);
; #pragma unroll
;         for (int r = 0; r < 16; ++r) {
;           float v = acc[j][r] * rstd[r] * g;
;           if (latent) {
;             const int s = (mrow + crow(r, hi)) & (SEQ - 1);
;             const int idx = (j < 2) ? (s >> 6) : (s & 63);
;             const float2 cs = rope[idx * 32 + fi];
;             const float pr = xor1(v);
;             v = v * cs.x + (((r32 & 1) != DBG_BREAK) ? pr * cs.y : -pr * cs.y);
;           }
;           acc[j][r] = v;
;         }
.LBB0_2889:
	s_or_b64 exec, exec, s[2:3]
	global_load_dword v146, v[136:137], off offset:256
	v_or_b32_e32 v142, v198, v170
	v_mul_f32_e32 v18, v18, v199
	v_lshlrev_b32_e32 v142, 5, v142
	s_movk_i32 s1, 0x480
	v_and_or_b32 v143, v142, s1, v169
	s_waitcnt vmcnt(0)
	v_mul_f32_e32 v18, v18, v146
	s_and_saveexec_b64 s[2:3], s[44:45]
	s_cbranch_execz .LBB0_2891
	v_lshlrev_b32_e32 v147, 3, v143
	global_load_dwordx2 v[244:245], v147, s[12:13] offset:256
	global_load_dwordx2 v[246:247], v147, s[12:13] offset:512
	global_load_dwordx2 v[248:249], v147, s[12:13] offset:768
	global_load_dwordx2 v[250:251], v147, s[12:13] offset:2048
	global_load_dwordx2 v[214:215], v147, s[12:13] offset:2304
	global_load_dwordx2 v[220:221], v147, s[12:13] offset:2560
	global_load_dwordx2 v[240:241], v147, s[12:13] offset:2816
	global_load_dwordx2 v[148:149], v147, s[12:13]
	v_mov_b32_e32 v147, v18
	v_mov_b32_e32 v152, v18
	s_nop 0
	v_mov_b32_dpp v147, v147 quad_perm:[1,0,3,2] row_mask:0xf bank_mask:0xf
	v_cndmask_b32_e64 v153, v147, -v147, s[38:39]
	s_waitcnt vmcnt(0)
	v_pk_mul_f32 v[148:149], v[152:153], v[148:149]
	s_nop 0
	v_add_f32_e32 v18, v148, v149

; DEVI int crow(int r, int hi) { return (r & 3) + 8 * (r >> 2) + 4 * hi; }
; DEVI float xor1(float v) { return dppf<0xB1, 0xF>(v, v); }
;   DEVI void operator()(f32x16* acc, int mrow, int pn, int r32, int hi, char* slice) const {
;     ...
;       for (int j = 0; j < 4; ++j) {
;         const float g = gain[j * 32 + r32];
;         const int fi = (j & 1) * 16 + (r32 >> 1);
; #pragma unroll
;         for (int r = 0; r < 16; ++r) {
;           float v = acc[j][r] * rstd[r] * g;
;           if (latent) {
;             const int s = (mrow + crow(r, hi)) & (SEQ - 1);
;             const int idx = (j < 2) ? (s >> 6) : (s & 63);
;             const float2 cs = rope[idx * 32 + fi];
;             const float pr = xor1(v);
;             v = v * cs.x + (((r32 & 1) != DBG_BREAK) ? pr * cs.y : -pr * cs.y);
;           }
;           acc[j][r] = v;
;         }
.LBB0_2897:
	s_or_b64 exec, exec, s[2:3]
	v_mul_f32_e32 v22, v22, v158
	v_mul_f32_e32 v22, v22, v146
	s_and_saveexec_b64 s[2:3], s[44:45]
	s_cbranch_execz .LBB0_2899
	v_lshlrev_b32_e32 v147, 3, v143
	v_mov_b32_e32 v148, v250
	v_mov_b32_e32 v149, v251
	v_mov_b32_e32 v147, v22
	v_mov_b32_e32 v152, v22
	s_nop 0
	v_mov_b32_dpp v147, v147 quad_perm:[1,0,3,2] row_mask:0xf bank_mask:0xf
	v_cndmask_b32_e64 v153, v147, -v147, s[38:39]
	s_waitcnt vmcnt(0)
	v_pk_mul_f32 v[148:149], v[152:153], v[148:149]
	s_nop 0
	v_add_f32_e32 v22, v148, v149
.LBB0_2899:
	s_or_b64 exec, exec, s[2:3]
	v_mul_f32_e32 v23, v23, v159
	v_mul_f32_e32 v23, v23, v146
	s_and_saveexec_b64 s[2:3], s[44:45]
	s_cbranch_execz .LBB0_2901
	v_lshlrev_b32_e32 v147, 3, v143
	v_mov_b32_e32 v148, v214
	v_mov_b32_e32 v149, v215
	v_mov_b32_e32 v147, v23
	v_mov_b32_e32 v152, v23
	s_nop 0
	v_mov_b32_dpp v147, v147 quad_perm:[1,0,3,2] row_mask:0xf bank_mask:0xf
	v_cndmask_b32_e64 v153, v147, -v147, s[38:39]
	s_waitcnt vmcnt(0)
	v_pk_mul_f32 v[148:149], v[152:153], v[148:149]
	s_nop 0
	v_add_f32_e32 v23, v148, v149
.LBB0_2901:
	s_or_b64 exec, exec, s[2:3]
	v_mul_f32_e32 v24, v24, v154
	v_mul_f32_e32 v24, v24, v146
	s_and_saveexec_b64 s[2:3], s[44:45]
	s_cbranch_execz .LBB0_2903
	v_lshlrev_b32_e32 v147, 3, v143
	v_mov_b32_e32 v148, v220
	v_mov_b32_e32 v149, v221
	v_mov_b32_e32 v147, v24
	v_mov_b32_e32 v152, v24
	s_nop 0
	v_mov_b32_dpp v147, v147 quad_perm:[1,0,3,2] row_mask:0xf bank_mask:0xf
	v_cndmask_b32_e64 v153, v147, -v147, s[38:39]
	s_waitcnt vmcnt(0)
	v_pk_mul_f32 v[148:149], v[152:153], v[148:149]
	s_nop 0
	v_add_f32_e32 v24, v148, v149
.LBB0_2903:
	s_or_b64 exec, exec, s[2:3]
	v_mul_f32_e32 v25, v25, v155
	v_mul_f32_e32 v25, v25, v146
	s_and_saveexec_b64 s[2:3], s[44:45]
	s_cbranch_execz .LBB0_2905
	v_lshlrev_b32_e32 v147, 3, v143
	v_mov_b32_e32 v148, v240
	v_mov_b32_e32 v149, v241
	v_mov_b32_e32 v147, v25
	v_mov_b32_e32 v152, v25
	s_nop 0
	v_mov_b32_dpp v147, v147 quad_perm:[1,0,3,2] row_mask:0xf bank_mask:0xf
	v_cndmask_b32_e64 v153, v147, -v147, s[38:39]
	s_waitcnt vmcnt(0)
	v_pk_mul_f32 v[148:149], v[152:153], v[148:149]
	s_nop 0
	v_add_f32_e32 v25, v148, v149
.LBB0_2905:
	s_or_b64 exec, exec, s[2:3]
	v_mul_f32_e32 v26, v26, v151
	v_mul_f32_e32 v26, v26, v146
	s_and_saveexec_b64 s[2:3], s[44:45]
	s_cbranch_execz .LBB0_2907
	v_lshlrev_b32_e32 v148, 3, v143
	v_mov_b32_e32 v149, v1
	v_lshl_add_u64 v[148:149], s[12:13], 0, v[148:149]
	v_add_co_u32_e32 v148, vcc, 0x1000, v148
	v_mov_b32_e32 v147, v26
	s_nop 0
	v_addc_co_u32_e32 v149, vcc, 0, v149, vcc
	global_load_dwordx2 v[244:245], v[148:149], off offset:256
	global_load_dwordx2 v[246:247], v[148:149], off offset:512
	global_load_dwordx2 v[248:249], v[148:149], off offset:768
	global_load_dwordx2 v[250:251], v[148:149], off offset:2048
	global_load_dwordx2 v[214:215], v[148:149], off offset:2304
	global_load_dwordx2 v[220:221], v[148:149], off offset:2560
	global_load_dwordx2 v[240:241], v[148:149], off offset:2816
	global_load_dwordx2 v[148:149], v[148:149], off
	v_mov_b32_dpp v147, v147 quad_perm:[1,0,3,2] row_mask:0xf bank_mask:0xf
	v_cndmask_b32_e64 v153, v147, -v147, s[38:39]
	v_mov_b32_e32 v152, v26
	s_waitcnt vmcnt(0)
	v_pk_mul_f32 v[148:149], v[152:153], v[148:149]
	s_nop 0
	v_add_f32_e32 v26, v148, v149

; DEVI int crow(int r, int hi) { return (r & 3) + 8 * (r >> 2) + 4 * hi; }
; DEVI float xor1(float v) { return dppf<0xB1, 0xF>(v, v); }
;   DEVI void operator()(f32x16* acc, int mrow, int pn, int r32, int hi, char* slice) const {
;     ...
;       for (int j = 0; j < 4; ++j) {
;         const float g = gain[j * 32 + r32];
;         const int fi = (j & 1) * 16 + (r32 >> 1);
; #pragma unroll
;         for (int r = 0; r < 16; ++r) {
;           float v = acc[j][r] * rstd[r] * g;
;           if (latent) {
;             const int s = (mrow + crow(r, hi)) & (SEQ - 1);
;             const int idx = (j < 2) ? (s >> 6) : (s & 63);
;             const float2 cs = rope[idx * 32 + fi];
;             const float pr = xor1(v);
;             v = v * cs.x + (((r32 & 1) != DBG_BREAK) ? pr * cs.y : -pr * cs.y);
;           }
;           acc[j][r] = v;
;         }
.LBB0_2913:
	s_or_b64 exec, exec, s[2:3]
	v_mul_f32_e32 v30, v30, v141
	v_mul_f32_e32 v30, v30, v146
	s_and_saveexec_b64 s[2:3], s[44:45]
	s_cbranch_execz .LBB0_2915
	v_lshlrev_b32_e32 v148, 3, v143
	v_mov_b32_e32 v149, v1
	v_lshl_add_u64 v[148:149], s[12:13], 0, v[148:149]
	v_add_co_u32_e32 v148, vcc, 0x1000, v148
	v_mov_b32_e32 v147, v30
	s_nop 0
	v_addc_co_u32_e32 v149, vcc, 0, v149, vcc
	v_mov_b32_e32 v148, v250
	v_mov_b32_e32 v149, v251
	v_mov_b32_dpp v147, v147 quad_perm:[1,0,3,2] row_mask:0xf bank_mask:0xf
	v_cndmask_b32_e64 v153, v147, -v147, s[38:39]
	v_mov_b32_e32 v152, v30
	s_waitcnt vmcnt(0)
	v_pk_mul_f32 v[148:149], v[152:153], v[148:149]
	s_nop 0
	v_add_f32_e32 v30, v148, v149
.LBB0_2915:
	s_or_b64 exec, exec, s[2:3]
	v_mul_f32_e32 v31, v31, v140
	v_mul_f32_e32 v31, v31, v146
	s_and_saveexec_b64 s[2:3], s[44:45]
	s_cbranch_execz .LBB0_2917
	v_lshlrev_b32_e32 v148, 3, v143
	v_mov_b32_e32 v149, v1
	v_lshl_add_u64 v[148:149], s[12:13], 0, v[148:149]
	v_add_co_u32_e32 v148, vcc, 0x1000, v148
	v_mov_b32_e32 v147, v31
	s_nop 0
	v_addc_co_u32_e32 v149, vcc, 0, v149, vcc
	v_mov_b32_e32 v148, v214
	v_mov_b32_e32 v149, v215
	v_mov_b32_dpp v147, v147 quad_perm:[1,0,3,2] row_mask:0xf bank_mask:0xf
	v_cndmask_b32_e64 v153, v147, -v147, s[38:39]
	v_mov_b32_e32 v152, v31
	s_waitcnt vmcnt(0)
	v_pk_mul_f32 v[148:149], v[152:153], v[148:149]
	s_nop 0
	v_add_f32_e32 v31, v148, v149
.LBB0_2917:
	s_or_b64 exec, exec, s[2:3]
	v_mul_f32_e32 v32, v32, v139
	v_mul_f32_e32 v32, v32, v146
	s_and_saveexec_b64 s[2:3], s[44:45]
	s_cbranch_execz .LBB0_2919
	v_lshlrev_b32_e32 v148, 3, v143
	v_mov_b32_e32 v149, v1
	v_lshl_add_u64 v[148:149], s[12:13], 0, v[148:149]
	v_add_co_u32_e32 v148, vcc, 0x1000, v148
	v_mov_b32_e32 v147, v32
	s_nop 0
	v_addc_co_u32_e32 v149, vcc, 0, v149, vcc
	v_mov_b32_e32 v148, v220
	v_mov_b32_e32 v149, v221
	v_mov_b32_dpp v147, v147 quad_perm:[1,0,3,2] row_mask:0xf bank_mask:0xf
	v_cndmask_b32_e64 v153, v147, -v147, s[38:39]
	v_mov_b32_e32 v152, v32
	s_waitcnt vmcnt(0)
	v_pk_mul_f32 v[148:149], v[152:153], v[148:149]
	s_nop 0
	v_add_f32_e32 v32, v148, v149
.LBB0_2919:
	s_or_b64 exec, exec, s[2:3]
	v_mul_f32_e32 v33, v33, v138
	v_mul_f32_e32 v33, v33, v146
	s_and_saveexec_b64 s[2:3], s[44:45]
	s_cbranch_execz .LBB0_2921
	v_lshlrev_b32_e32 v146, 3, v143
	v_mov_b32_e32 v147, v1
	v_lshl_add_u64 v[146:147], s[12:13], 0, v[146:147]
	v_add_co_u32_e32 v146, vcc, 0x1000, v146
	v_mov_b32_e32 v143, v33
	s_nop 0
	v_addc_co_u32_e32 v147, vcc, 0, v147, vcc
	v_mov_b32_e32 v146, v240
	v_mov_b32_e32 v147, v241
	v_mov_b32_dpp v143, v143 quad_perm:[1,0,3,2] row_mask:0xf bank_mask:0xf
	v_cndmask_b32_e64 v149, v143, -v143, s[38:39]
	v_mov_b32_e32 v148, v33
	s_waitcnt vmcnt(0)
	v_pk_mul_f32 v[146:147], v[148:149], v[146:147]
	s_nop 0
	v_add_f32_e32 v33, v146, v147
.LBB0_2921:
	s_or_b64 exec, exec, s[2:3]
	global_load_dword v137, v[136:137], off offset:384
	v_mul_f32_e32 v2, v2, v199
	v_and_or_b32 v136, v142, s1, v171
	s_waitcnt vmcnt(0)
	v_mul_f32_e32 v2, v2, v137
	s_and_saveexec_b64 s[2:3], s[44:45]
	s_cbranch_execz .LBB0_2923
	v_lshlrev_b32_e32 v142, 3, v136
	global_load_dwordx2 v[244:245], v142, s[12:13] offset:256
	global_load_dwordx2 v[246:247], v142, s[12:13] offset:512
	global_load_dwordx2 v[248:249], v142, s[12:13] offset:768
	global_load_dwordx2 v[250:251], v142, s[12:13] offset:2048
	global_load_dwordx2 v[214:215], v142, s[12:13] offset:2304
	global_load_dwordx2 v[220:221], v142, s[12:13] offset:2560
	global_load_dwordx2 v[240:241], v142, s[12:13] offset:2816
	global_load_dwordx2 v[142:143], v142, s[12:13]
	v_mov_b32_e32 v146, v2
	s_nop 1
	v_mov_b32_dpp v146, v146 quad_perm:[1,0,3,2] row_mask:0xf bank_mask:0xf
	v_cndmask_b32_e64 v147, v146, -v146, s[38:39]
	v_mov_b32_e32 v146, v2
	s_waitcnt vmcnt(0)
	v_pk_mul_f32 v[142:143], v[146:147], v[142:143]
	s_nop 0
	v_add_f32_e32 v2, v142, v143

; DEVI int crow(int r, int hi) { return (r & 3) + 8 * (r >> 2) + 4 * hi; }
; DEVI float xor1(float v) { return dppf<0xB1, 0xF>(v, v); }
;   DEVI void operator()(f32x16* acc, int mrow, int pn, int r32, int hi, char* slice) const {
;     ...
;       for (int j = 0; j < 4; ++j) {
;         const float g = gain[j * 32 + r32];
;         const int fi = (j & 1) * 16 + (r32 >> 1);
; #pragma unroll
;         for (int r = 0; r < 16; ++r) {
;           float v = acc[j][r] * rstd[r] * g;
;           if (latent) {
;             const int s = (mrow + crow(r, hi)) & (SEQ - 1);
;             const int idx = (j < 2) ? (s >> 6) : (s & 63);
;             const float2 cs = rope[idx * 32 + fi];
;             const float pr = xor1(v);
;             v = v * cs.x + (((r32 & 1) != DBG_BREAK) ? pr * cs.y : -pr * cs.y);
;           }
;           acc[j][r] = v;
;         }
.LBB0_2929:
	s_or_b64 exec, exec, s[2:3]
	v_mul_f32_e32 v6, v6, v158
	v_mul_f32_e32 v6, v6, v137
	s_and_saveexec_b64 s[2:3], s[44:45]
	s_cbranch_execz .LBB0_2931
	v_lshlrev_b32_e32 v142, 3, v136
	v_mov_b32_e32 v142, v250
	v_mov_b32_e32 v143, v251
	v_mov_b32_e32 v146, v6
	s_nop 1
	v_mov_b32_dpp v146, v146 quad_perm:[1,0,3,2] row_mask:0xf bank_mask:0xf
	v_cndmask_b32_e64 v147, v146, -v146, s[38:39]
	v_mov_b32_e32 v146, v6
	s_waitcnt vmcnt(0)
	v_pk_mul_f32 v[142:143], v[146:147], v[142:143]
	s_nop 0
	v_add_f32_e32 v6, v142, v143
.LBB0_2931:
	s_or_b64 exec, exec, s[2:3]
	v_mul_f32_e32 v7, v7, v159
	v_mul_f32_e32 v7, v7, v137
	s_and_saveexec_b64 s[2:3], s[44:45]
	s_cbranch_execz .LBB0_2933
	v_lshlrev_b32_e32 v142, 3, v136
	v_mov_b32_e32 v142, v214
	v_mov_b32_e32 v143, v215
	v_mov_b32_e32 v146, v7
	s_nop 1
	v_mov_b32_dpp v146, v146 quad_perm:[1,0,3,2] row_mask:0xf bank_mask:0xf
	v_cndmask_b32_e64 v147, v146, -v146, s[38:39]
	v_mov_b32_e32 v146, v7
	s_waitcnt vmcnt(0)
	v_pk_mul_f32 v[142:143], v[146:147], v[142:143]
	s_nop 0
	v_add_f32_e32 v7, v142, v143
.LBB0_2933:
	s_or_b64 exec, exec, s[2:3]
	v_mul_f32_e32 v8, v8, v154
	v_mul_f32_e32 v8, v8, v137
	s_and_saveexec_b64 s[2:3], s[44:45]
	s_cbranch_execz .LBB0_2935
	v_lshlrev_b32_e32 v142, 3, v136
	v_mov_b32_e32 v142, v220
	v_mov_b32_e32 v143, v221
	v_mov_b32_e32 v146, v8
	s_nop 1
	v_mov_b32_dpp v146, v146 quad_perm:[1,0,3,2] row_mask:0xf bank_mask:0xf
	v_cndmask_b32_e64 v147, v146, -v146, s[38:39]
	v_mov_b32_e32 v146, v8
	s_waitcnt vmcnt(0)
	v_pk_mul_f32 v[142:143], v[146:147], v[142:143]
	s_nop 0
	v_add_f32_e32 v8, v142, v143
.LBB0_2935:
	s_or_b64 exec, exec, s[2:3]
	v_mul_f32_e32 v9, v9, v155
	v_mul_f32_e32 v9, v9, v137
	s_and_saveexec_b64 s[2:3], s[44:45]
	s_cbranch_execz .LBB0_2937
	v_lshlrev_b32_e32 v142, 3, v136
	v_mov_b32_e32 v142, v240
	v_mov_b32_e32 v143, v241
	v_mov_b32_e32 v146, v9
	s_nop 1
	v_mov_b32_dpp v146, v146 quad_perm:[1,0,3,2] row_mask:0xf bank_mask:0xf
	v_cndmask_b32_e64 v147, v146, -v146, s[38:39]
	v_mov_b32_e32 v146, v9
	s_waitcnt vmcnt(0)
	v_pk_mul_f32 v[142:143], v[146:147], v[142:143]
	s_nop 0
	v_add_f32_e32 v9, v142, v143
.LBB0_2937:
	s_or_b64 exec, exec, s[2:3]
	v_mul_f32_e32 v10, v10, v151
	v_mul_f32_e32 v10, v10, v137
	s_and_saveexec_b64 s[2:3], s[44:45]
	s_cbranch_execz .LBB0_2939
	v_lshlrev_b32_e32 v142, 3, v136
	v_mov_b32_e32 v143, v1
	v_lshl_add_u64 v[142:143], s[12:13], 0, v[142:143]
	v_add_co_u32_e32 v142, vcc, 0x1000, v142
	v_mov_b32_e32 v146, v10
	s_nop 0
	v_addc_co_u32_e32 v143, vcc, 0, v143, vcc
	global_load_dwordx2 v[244:245], v[142:143], off offset:256
	global_load_dwordx2 v[246:247], v[142:143], off offset:512
	global_load_dwordx2 v[248:249], v[142:143], off offset:768
	global_load_dwordx2 v[250:251], v[142:143], off offset:2048
	global_load_dwordx2 v[214:215], v[142:143], off offset:2304
	global_load_dwordx2 v[220:221], v[142:143], off offset:2560
	global_load_dwordx2 v[240:241], v[142:143], off offset:2816
	global_load_dwordx2 v[142:143], v[142:143], off
	v_mov_b32_dpp v146, v146 quad_perm:[1,0,3,2] row_mask:0xf bank_mask:0xf
	v_cndmask_b32_e64 v147, v146, -v146, s[38:39]
	v_mov_b32_e32 v146, v10
	s_waitcnt vmcnt(0)
	v_pk_mul_f32 v[142:143], v[146:147], v[142:143]
	s_nop 0
	v_add_f32_e32 v10, v142, v143

; DEVI int crow(int r, int hi) { return (r & 3) + 8 * (r >> 2) + 4 * hi; }
; DEVI float xor1(float v) { return dppf<0xB1, 0xF>(v, v); }
;   DEVI void operator()(f32x16* acc, int mrow, int pn, int r32, int hi, char* slice) const {
;     ...
;       for (int j = 0; j < 4; ++j) {
;         const float g = gain[j * 32 + r32];
;         const int fi = (j & 1) * 16 + (r32 >> 1);
; #pragma unroll
;         for (int r = 0; r < 16; ++r) {
;           float v = acc[j][r] * rstd[r] * g;
;           if (latent) {
;             const int s = (mrow + crow(r, hi)) & (SEQ - 1);
;             const int idx = (j < 2) ? (s >> 6) : (s & 63);
;             const float2 cs = rope[idx * 32 + fi];
;             const float pr = xor1(v);
;             v = v * cs.x + (((r32 & 1) != DBG_BREAK) ? pr * cs.y : -pr * cs.y);
;           }
;           acc[j][r] = v;
;         }
.LBB0_2945:
	s_or_b64 exec, exec, s[2:3]
	v_mul_f32_e32 v14, v14, v141
	v_mul_f32_e32 v14, v14, v137
	s_and_saveexec_b64 s[2:3], s[44:45]
	s_cbranch_execz .LBB0_2947
	v_lshlrev_b32_e32 v142, 3, v136
	v_mov_b32_e32 v143, v1
	v_lshl_add_u64 v[142:143], s[12:13], 0, v[142:143]
	v_add_co_u32_e32 v142, vcc, 0x1000, v142
	v_mov_b32_e32 v141, v14
	s_nop 0
	v_addc_co_u32_e32 v143, vcc, 0, v143, vcc
	v_mov_b32_e32 v142, v250
	v_mov_b32_e32 v143, v251
	v_mov_b32_dpp v141, v141 quad_perm:[1,0,3,2] row_mask:0xf bank_mask:0xf
	v_cndmask_b32_e64 v145, v141, -v141, s[38:39]
	v_mov_b32_e32 v144, v14
	s_waitcnt vmcnt(0)
	v_pk_mul_f32 v[142:143], v[144:145], v[142:143]
	s_nop 0
	v_add_f32_e32 v14, v142, v143
.LBB0_2947:
	s_or_b64 exec, exec, s[2:3]
	v_mul_f32_e32 v15, v15, v140
	v_mul_f32_e32 v15, v15, v137
	s_and_saveexec_b64 s[2:3], s[44:45]
	s_cbranch_execz .LBB0_2949
	v_lshlrev_b32_e32 v140, 3, v136
	v_mov_b32_e32 v141, v1
	v_lshl_add_u64 v[140:141], s[12:13], 0, v[140:141]
	v_add_co_u32_e32 v140, vcc, 0x1000, v140
	v_mov_b32_e32 v142, v15
	s_nop 0
	v_addc_co_u32_e32 v141, vcc, 0, v141, vcc
	v_mov_b32_e32 v140, v214
	v_mov_b32_e32 v141, v215
	v_mov_b32_dpp v142, v142 quad_perm:[1,0,3,2] row_mask:0xf bank_mask:0xf
	v_cndmask_b32_e64 v143, v142, -v142, s[38:39]
	v_mov_b32_e32 v142, v15
	s_waitcnt vmcnt(0)
	v_pk_mul_f32 v[140:141], v[142:143], v[140:141]
	s_nop 0
	v_add_f32_e32 v15, v140, v141
.LBB0_2949:
	s_or_b64 exec, exec, s[2:3]
	v_mul_f32_e32 v16, v16, v139
	v_mul_f32_e32 v16, v16, v137
	s_and_saveexec_b64 s[2:3], s[44:45]
	s_cbranch_execz .LBB0_2951
	v_lshlrev_b32_e32 v140, 3, v136
	v_mov_b32_e32 v141, v1
	v_lshl_add_u64 v[140:141], s[12:13], 0, v[140:141]
	v_add_co_u32_e32 v140, vcc, 0x1000, v140
	v_mov_b32_e32 v139, v16
	s_nop 0
	v_addc_co_u32_e32 v141, vcc, 0, v141, vcc
	v_mov_b32_e32 v140, v220
	v_mov_b32_e32 v141, v221
	v_mov_b32_dpp v139, v139 quad_perm:[1,0,3,2] row_mask:0xf bank_mask:0xf
	v_cndmask_b32_e64 v143, v139, -v139, s[38:39]
	v_mov_b32_e32 v142, v16
	s_waitcnt vmcnt(0)
	v_pk_mul_f32 v[140:141], v[142:143], v[140:141]
	s_nop 0
	v_add_f32_e32 v16, v140, v141
.LBB0_2951:
	s_or_b64 exec, exec, s[2:3]
	v_mul_f32_e32 v17, v17, v138
	v_mul_f32_e32 v17, v17, v137
	s_and_saveexec_b64 s[2:3], s[44:45]
	s_cbranch_execz .LBB0_2953
	v_lshlrev_b32_e32 v136, 3, v136
	v_mov_b32_e32 v137, v1
	v_lshl_add_u64 v[136:137], s[12:13], 0, v[136:137]
	v_add_co_u32_e32 v136, vcc, 0x1000, v136
	v_mov_b32_e32 v138, v17
	s_nop 0
	v_addc_co_u32_e32 v137, vcc, 0, v137, vcc
	v_mov_b32_e32 v136, v240
	v_mov_b32_e32 v137, v241
	v_mov_b32_dpp v138, v138 quad_perm:[1,0,3,2] row_mask:0xf bank_mask:0xf
	v_cndmask_b32_e64 v139, v138, -v138, s[38:39]
	v_mov_b32_e32 v138, v17
	s_waitcnt vmcnt(0)
	v_pk_mul_f32 v[136:137], v[138:139], v[136:137]
	s_nop 0
	v_add_f32_e32 v17, v136, v137
